# merge: gate tiles staged through free LDS holes by LDS-DMA and read with ds_read_b64, replacing the strided 8-byte global gate loads
# speedup vs baseline: 1.0102x; 1.0102x over previous
.LBB0_110:
	s_lshl_b32 s50, s4, 7
	s_mul_i32 s4, s5, 0x48000
	s_ashr_i32 s51, s50, 31
	s_mul_i32 s1, s3, 0x48000
	s_mul_i32 s0, s5, 0x60
	s_ashr_i32 s5, s4, 31
	s_lshl_b64 s[52:53], s[50:51], 10
	s_ashr_i32 s3, s1, 31
	v_readlane_b32 s16, v249, 39
	v_readlane_b32 s17, v249, 40
	s_add_u32 s12, s16, s1
	s_addc_u32 s14, s17, s3
	s_add_u32 s1, s16, s4
	s_addc_u32 s11, s17, s5
	s_lshl_b32 s2, s2, 7
	s_ashr_i32 s3, s2, 31
	s_lshl_b64 s[54:55], s[2:3], 10
	v_readlane_b32 s2, v247, 39
	v_readlane_b32 s3, v247, 40
	s_mul_i32 s34, s0, 0x3700
	s_lshl_b32 s35, s50, 1
	s_add_u32 s34, s34, s35
	s_add_u32 s34, s34, 0x9801f00
	s_add_u32 s30, s2, s34
	s_addc_u32 s31, s3, 0
	v_lshrrev_b32_e32 v243, 6, v167
	v_lshrrev_b32_e32 v170, 4, v167
	v_readfirstlane_b32 s36, v243
	v_and_b32_e32 v224, 15, v167
	v_xor_b32_e32 v224, v224, v170
	v_lshlrev_b32_e32 v224, 4, v224
	v_mul_u32_u24_e32 v170, 0x3700, v170
	v_add_u32_e32 v170, v170, v224
	s_lshl_b32 s36, s36, 10
	v_and_b32_e32 v224, 15, v167
	v_bfe_u32 v225, v167, 5, 1
	v_bfe_u32 v242, v167, 6, 1
	v_lshl_or_b32 v225, v242, 3, v225
	v_xor_b32_e32 v225, v225, v224
	v_lshlrev_b32_e32 v225, 4, v225
	v_bfe_u32 v242, v167, 4, 1
	v_lshl_or_b32 v225, v242, 3, v225
	v_bfe_u32 v242, v167, 7, 1
	v_lshlrev_b32_e32 v243, 8, v224
	v_lshlrev_b32_e32 v244, 12, v242
	v_add_u32_e32 v244, 0x12000, v244
	v_add_u32_e32 v244, v244, v243
	v_add_u32_e32 v244, v244, v225
	v_mul_u32_u24_e32 v242, 0xd000, v242
	v_sub_u32_e32 v242, 0x10000, v242
	v_add_u32_e32 v242, v242, v243
	v_add_u32_e32 v224, v242, v225
	v_xor_b32_e32 v225, 32, v224
	v_xor_b32_e32 v242, 64, v224
	v_xor_b32_e32 v243, 0x60, v224
	v_xor_b32_e32 v245, 32, v244
	v_xor_b32_e32 v246, 64, v244
	v_xor_b32_e32 v172, 0x60, v244
	v_add_u32_e32 v8, s0, v143
	v_or_b32_e32 v0, s50, v144
	v_mov_b64_e32 v[2:3], s[2:3]
	s_movk_i32 s15, 0x3700
	v_ashrrev_i32_e32 v1, 31, v0
	v_mad_i64_i32 v[4:5], s[2:3], v8, s15, v[2:3]
	v_add_u32_e32 v6, 16, v8
	v_add_u32_e32 v8, 32, v8
	v_mad_i64_i32 v[6:7], s[2:3], v6, s15, v[2:3]
	v_mad_i64_i32 v[2:3], s[2:3], v8, s15, v[2:3]
	s_and_b64 s[2:3], s[48:49], exec
	v_lshlrev_b64 v[0:1], 1, v[0:1]
	v_lshl_add_u64 v[4:5], v[4:5], 0, v[0:1]
	s_mov_b64 s[2:3], 0x9801f00
	v_lshl_add_u64 v[84:85], v[4:5], 0, s[2:3]
	v_lshl_add_u64 v[4:5], v[6:7], 0, v[0:1]
	v_lshl_add_u64 v[0:1], v[2:3], 0, v[0:1]
	v_mov_b32_e32 v48, v153
	v_mov_b32_e32 v49, v153
	v_lshl_add_u64 v[88:89], v[0:1], 0, s[2:3]
	v_mov_b32_e32 v50, v153
	v_mov_b32_e32 v51, v153
	v_mov_b64_e32 v[8:9], v[48:49]
	v_mov_b64_e32 v[12:13], v[48:49]
	v_mov_b64_e32 v[16:17], v[48:49]
	v_mov_b64_e32 v[20:21], v[48:49]
	v_mov_b64_e32 v[24:25], v[48:49]
	v_mov_b64_e32 v[28:29], v[48:49]
	v_mov_b64_e32 v[32:33], v[48:49]
	v_mov_b64_e32 v[36:37], v[48:49]
	v_mov_b64_e32 v[40:41], v[48:49]
	v_mov_b64_e32 v[44:45], v[48:49]
	v_mov_b64_e32 v[0:1], v[48:49]
	v_lshl_add_u64 v[80:81], v[54:55], 0, s[4:5]
	s_cselect_b32 s14, s14, 0
	s_cselect_b32 s15, s12, 0
	v_lshl_add_u64 v[82:83], v[58:59], 0, s[52:53]
	v_lshl_add_u64 v[86:87], v[4:5], 0, s[2:3]
	v_lshl_add_u64 v[90:91], v[60:61], 0, s[4:5]
	v_lshl_add_u64 v[92:93], v[62:63], 0, s[52:53]
	v_mov_b64_e32 v[10:11], v[50:51]
	v_mov_b64_e32 v[14:15], v[50:51]
	v_mov_b64_e32 v[18:19], v[50:51]
	v_mov_b64_e32 v[22:23], v[50:51]
	v_mov_b64_e32 v[26:27], v[50:51]
	v_mov_b64_e32 v[30:31], v[50:51]
	v_mov_b64_e32 v[34:35], v[50:51]
	v_mov_b64_e32 v[38:39], v[50:51]
	v_mov_b64_e32 v[42:43], v[50:51]
	v_mov_b64_e32 v[46:47], v[50:51]
	v_mov_b64_e32 v[2:3], v[50:51]
	s_branch .LBB0_112

.LBB0_112:
	s_lshl_b32 s2, s10, 10
	s_lshl_b32 s16, s10, 9
	s_add_i32 s12, s2, 0x400
	s_cmp_lg_u32 s10, 2
	s_cselect_b64 s[2:3], -1, 0
	s_and_b64 s[4:5], s[2:3], exec
	s_cselect_b32 s4, s12, 0x800
	s_lshl_b32 s12, s10, 11
	v_lshl_add_u64 v[4:5], v[84:85], 0, s[12:13]
	s_lshl_b32 s4, s4, 1
	s_mov_b32 s5, s13
	v_lshl_add_u64 v[6:7], v[84:85], 0, s[4:5]
	s_cmp_eq_u32 s10, 0
	s_cbranch_scc0 .Lmg_reuse
	s_add_u32 m0, s36, 0x10000
	s_add_u32 s34, s30, 0x0
	s_addc_u32 s35, s31, 0
	global_load_lds_dwordx4 v170, s[34:35]
	s_add_u32 m0, s36, 0x11000
	s_add_u32 s34, s30, 0x37000
	s_addc_u32 s35, s31, 0
	global_load_lds_dwordx4 v170, s[34:35]
	s_add_u32 m0, s36, 0x12000
	s_add_u32 s34, s30, 0x6e000
	s_addc_u32 s35, s31, 0
	global_load_lds_dwordx4 v170, s[34:35]
	s_add_u32 m0, s36, 0x3000
	s_add_u32 s34, s30, 0xa5000
	s_addc_u32 s35, s31, 0
	global_load_lds_dwordx4 v170, s[34:35]
	s_add_u32 m0, s36, 0xb000
	s_add_u32 s34, s30, 0xdc000
	s_addc_u32 s35, s31, 0
	global_load_lds_dwordx4 v170, s[34:35]
	s_add_u32 m0, s36, 0x13000
	s_add_u32 s34, s30, 0x113000
	s_addc_u32 s35, s31, 0
	global_load_lds_dwordx4 v170, s[34:35]
	s_waitcnt vmcnt(0)
	s_barrier
	v_add_u32_e32 v65, v224, v244
	v_add_u32_e32 v67, v225, v245
	v_add_u32_e32 v69, v242, v246
	v_add_u32_e32 v71, v243, v172
	v_lshrrev_b32_e32 v65, 1, v65
	v_lshrrev_b32_e32 v67, 1, v67
	v_lshrrev_b32_e32 v69, 1, v69
	v_lshrrev_b32_e32 v71, 1, v71
	ds_read_b64 v[140:141], v224
	ds_read_b64 v[106:107], v225
	ds_read_b64 v[114:115], v242
	ds_read_b64 v[122:123], v243
	ds_read_b64 v[116:117], v244
	ds_read_b64 v[108:109], v245
	ds_read_b64 v[100:101], v246
	ds_read_b64 v[96:97], v172
	ds_read_b64 v[130:131], v65
	ds_read_b64 v[138:139], v67
	ds_read_b64 v[132:133], v69
	ds_read_b64 v[124:125], v71
	s_waitcnt lgkmcnt(0)
	s_barrier
	s_add_u32 m0, s36, 0x10000
	s_add_u32 s34, s30, 0x800
	s_addc_u32 s35, s31, 0
	global_load_lds_dwordx4 v170, s[34:35]
	s_add_u32 m0, s36, 0x11000
	s_add_u32 s34, s30, 0x37800
	s_addc_u32 s35, s31, 0
	global_load_lds_dwordx4 v170, s[34:35]
	s_add_u32 m0, s36, 0x12000
	s_add_u32 s34, s30, 0x6e800
	s_addc_u32 s35, s31, 0
	global_load_lds_dwordx4 v170, s[34:35]
	s_add_u32 m0, s36, 0x3000
	s_add_u32 s34, s30, 0xa5800
	s_addc_u32 s35, s31, 0
	global_load_lds_dwordx4 v170, s[34:35]
	s_add_u32 m0, s36, 0xb000
	s_add_u32 s34, s30, 0xdc800
	s_addc_u32 s35, s31, 0
	global_load_lds_dwordx4 v170, s[34:35]
	s_add_u32 m0, s36, 0x13000
	s_add_u32 s34, s30, 0x113800
	s_addc_u32 s35, s31, 0
	global_load_lds_dwordx4 v170, s[34:35]
	s_branch .Lmg_ld_done
.Lmg_reuse:
	v_mov_b32_e32 v140, v102
	v_mov_b32_e32 v106, v110
	v_mov_b32_e32 v114, v120
	v_mov_b32_e32 v122, v128
	v_mov_b32_e32 v130, v136
	v_mov_b32_e32 v138, v134
	v_mov_b32_e32 v132, v126
	v_mov_b32_e32 v124, v118
	v_mov_b32_e32 v116, v112
	v_mov_b32_e32 v108, v104
	v_mov_b32_e32 v100, v98
	v_mov_b32_e32 v96, v94
	v_mov_b32_e32 v141, v103
	v_mov_b32_e32 v107, v111
	v_mov_b32_e32 v115, v121
	v_mov_b32_e32 v123, v129
	v_mov_b32_e32 v131, v137
	v_mov_b32_e32 v139, v135
	v_mov_b32_e32 v133, v127
	v_mov_b32_e32 v125, v119
	v_mov_b32_e32 v117, v113
	v_mov_b32_e32 v109, v105
	v_mov_b32_e32 v101, v99
	v_mov_b32_e32 v97, v95
	s_cmp_eq_u32 s10, 1
	s_cbranch_scc0 .Lmg_ld_done
	s_barrier
	s_add_u32 m0, s36, 0x10000
	s_add_u32 s34, s30, 0x1000
	s_addc_u32 s35, s31, 0
	global_load_lds_dwordx4 v170, s[34:35]
	s_add_u32 m0, s36, 0x11000
	s_add_u32 s34, s30, 0x38000
	s_addc_u32 s35, s31, 0
	global_load_lds_dwordx4 v170, s[34:35]
	s_add_u32 m0, s36, 0x12000
	s_add_u32 s34, s30, 0x6f000
	s_addc_u32 s35, s31, 0
	global_load_lds_dwordx4 v170, s[34:35]
	s_add_u32 m0, s36, 0x3000
	s_add_u32 s34, s30, 0xa6000
	s_addc_u32 s35, s31, 0
	global_load_lds_dwordx4 v170, s[34:35]
	s_add_u32 m0, s36, 0xb000
	s_add_u32 s34, s30, 0xdd000
	s_addc_u32 s35, s31, 0
	global_load_lds_dwordx4 v170, s[34:35]
	s_add_u32 m0, s36, 0x13000
	s_add_u32 s34, s30, 0x114000
	s_addc_u32 s35, s31, 0
	global_load_lds_dwordx4 v170, s[34:35]

.LBB0_118:
	ds_read_b128 v[4:7], v150 offset:32768
	ds_read_b128 v[174:177], v150 offset:34816
	ds_read_b128 v[178:181], v150 offset:36864
	ds_read_b128 v[212:215], v151 offset:49152
	ds_read_b128 v[216:219], v151 offset:51200
	ds_read_b128 v[220:223], v151 offset:53248
	ds_read_b128 v[234:237], v151 offset:55296
	s_waitcnt lgkmcnt(0)
	v_mfma_f32_16x16x32_bf16 v[48:51], v[212:215], v[4:7], v[48:51]
	v_mfma_f32_16x16x32_bf16 v[8:11], v[216:219], v[4:7], v[8:11]
	v_mfma_f32_16x16x32_bf16 v[12:15], v[220:223], v[4:7], v[12:15]
	v_mfma_f32_16x16x32_bf16 v[4:7], v[234:237], v[4:7], v[16:19]
	v_mfma_f32_16x16x32_bf16 v[20:23], v[212:215], v[174:177], v[20:23]
	v_mfma_f32_16x16x32_bf16 v[24:27], v[216:219], v[174:177], v[24:27]
	v_mfma_f32_16x16x32_bf16 v[28:31], v[220:223], v[174:177], v[28:31]
	v_mfma_f32_16x16x32_bf16 v[32:35], v[234:237], v[174:177], v[32:35]
	v_mfma_f32_16x16x32_bf16 v[36:39], v[212:215], v[178:181], v[36:39]
	v_mfma_f32_16x16x32_bf16 v[40:43], v[216:219], v[178:181], v[40:43]
	v_mfma_f32_16x16x32_bf16 v[44:47], v[220:223], v[178:181], v[44:47]
	v_mfma_f32_16x16x32_bf16 v[174:177], v[234:237], v[178:181], v[0:3]
	ds_read_b128 v[16:19], v155 offset:32768
	ds_read_b128 v[178:181], v155 offset:34816
	ds_read_b128 v[212:215], v155 offset:36864
	ds_read_b128 v[216:219], v157 offset:49152
	ds_read_b128 v[220:223], v157 offset:51200
	ds_read_b128 v[234:237], v157 offset:53248
	ds_read_b128 v[238:241], v157 offset:55296
	s_waitcnt lgkmcnt(0)
	v_mfma_f32_16x16x32_bf16 v[0:3], v[216:219], v[16:19], v[48:51]
	s_waitcnt vmcnt(0)
	v_mfma_f32_16x16x32_bf16 v[8:11], v[220:223], v[16:19], v[8:11]
	v_mfma_f32_16x16x32_bf16 v[12:15], v[234:237], v[16:19], v[12:15]
	v_mfma_f32_16x16x32_bf16 v[16:19], v[238:241], v[16:19], v[4:7]
	v_mfma_f32_16x16x32_bf16 v[20:23], v[216:219], v[178:181], v[20:23]
	v_mfma_f32_16x16x32_bf16 v[24:27], v[220:223], v[178:181], v[24:27]
	v_mfma_f32_16x16x32_bf16 v[28:31], v[234:237], v[178:181], v[28:31]
	v_mfma_f32_16x16x32_bf16 v[32:35], v[238:241], v[178:181], v[32:35]
	v_mfma_f32_16x16x32_bf16 v[36:39], v[216:219], v[212:215], v[36:39]
	v_mfma_f32_16x16x32_bf16 v[40:43], v[220:223], v[212:215], v[40:43]
	v_mfma_f32_16x16x32_bf16 v[44:47], v[234:237], v[212:215], v[44:47]
	v_mfma_f32_16x16x32_bf16 v[4:7], v[238:241], v[212:215], v[174:177]
	s_not_b64 s[40:41], s[2:3]
	s_andn2_b64 vcc, exec, s[2:3]
	s_cbranch_vccnz .Lmg_last
	v_add_u32_e32 v65, v224, v244
	v_add_u32_e32 v67, v225, v245
	v_add_u32_e32 v69, v242, v246
	v_add_u32_e32 v71, v243, v172
	v_lshrrev_b32_e32 v65, 1, v65
	v_lshrrev_b32_e32 v67, 1, v67
	v_lshrrev_b32_e32 v69, 1, v69
	v_lshrrev_b32_e32 v71, 1, v71
	ds_read_b64 v[102:103], v224
	ds_read_b64 v[110:111], v225
	ds_read_b64 v[120:121], v242
	ds_read_b64 v[128:129], v243
	ds_read_b64 v[112:113], v244
	ds_read_b64 v[104:105], v245
	ds_read_b64 v[98:99], v246
	ds_read_b64 v[94:95], v172
	ds_read_b64 v[136:137], v65
	ds_read_b64 v[134:135], v67
	ds_read_b64 v[126:127], v69
	ds_read_b64 v[118:119], v71
	s_waitcnt lgkmcnt(0)
	v_lshlrev_b32_e32 v65, 16, v102
	v_and_b32_e32 v67, 0xffff0000, v102
	v_lshlrev_b32_e32 v69, 16, v103
	v_and_b32_e32 v71, 0xffff0000, v103
	v_mul_f32_e32 v65, 0xbfb8aa3b, v65
	v_mul_f32_e32 v67, 0xbfb8aa3b, v67
	v_mul_f32_e32 v69, 0xbfb8aa3b, v69
	v_mul_f32_e32 v71, 0xbfb8aa3b, v71
	v_exp_f32_e32 v65, v65
	v_exp_f32_e32 v67, v67
	v_exp_f32_e32 v69, v69
	v_exp_f32_e32 v71, v71
	v_add_f32_e32 v65, 1.0, v65
	v_add_f32_e32 v67, 1.0, v67
	v_add_f32_e32 v69, 1.0, v69
	v_add_f32_e32 v71, 1.0, v71
	v_min_f32_e32 v65, 0x49742400, v65
	v_min_f32_e32 v67, 0x49742400, v67
	v_min_f32_e32 v69, 0x49742400, v69
	v_min_f32_e32 v71, 0x49742400, v71
	v_mul_f32_e32 v48, v0, v65
	v_mul_f32_e32 v49, v1, v67
	v_mul_f32_e32 v50, v2, v69
	v_mul_f32_e32 v51, v3, v71
	v_lshlrev_b32_e32 v65, 16, v140
	v_and_b32_e32 v67, 0xffff0000, v140
	v_lshlrev_b32_e32 v69, 16, v141
	v_and_b32_e32 v71, 0xffff0000, v141
	v_mul_f32_e32 v65, 0xbfb8aa3b, v65
	v_mul_f32_e32 v67, 0xbfb8aa3b, v67
	v_mul_f32_e32 v69, 0xbfb8aa3b, v69
	v_mul_f32_e32 v71, 0xbfb8aa3b, v71
	v_exp_f32_e32 v65, v65
	v_exp_f32_e32 v67, v67
	v_exp_f32_e32 v69, v69
	v_exp_f32_e32 v71, v71
	v_add_f32_e32 v65, 1.0, v65
	v_add_f32_e32 v67, 1.0, v67
	v_add_f32_e32 v69, 1.0, v69
	v_add_f32_e32 v71, 1.0, v71
	v_rcp_f32_e32 v65, v65
	v_rcp_f32_e32 v67, v67
	v_rcp_f32_e32 v69, v69
	v_rcp_f32_e32 v71, v71
	v_max_f32_e32 v65, 0x358637bd, v65
	v_max_f32_e32 v67, 0x358637bd, v67
	v_max_f32_e32 v69, 0x358637bd, v69
	v_max_f32_e32 v71, 0x358637bd, v71
	v_mul_f32_e32 v48, v48, v65
	v_mul_f32_e32 v49, v49, v67
	v_mul_f32_e32 v50, v50, v69
	v_mul_f32_e32 v51, v51, v71
	v_lshlrev_b32_e32 v65, 16, v110
	v_and_b32_e32 v67, 0xffff0000, v110
	v_lshlrev_b32_e32 v69, 16, v111
	v_and_b32_e32 v71, 0xffff0000, v111
	v_mul_f32_e32 v65, 0xbfb8aa3b, v65
	v_mul_f32_e32 v67, 0xbfb8aa3b, v67
	v_mul_f32_e32 v69, 0xbfb8aa3b, v69
	v_mul_f32_e32 v71, 0xbfb8aa3b, v71
	v_exp_f32_e32 v65, v65
	v_exp_f32_e32 v67, v67
	v_exp_f32_e32 v69, v69
	v_exp_f32_e32 v71, v71
	v_add_f32_e32 v65, 1.0, v65
	v_add_f32_e32 v67, 1.0, v67
	v_add_f32_e32 v69, 1.0, v69
	v_add_f32_e32 v71, 1.0, v71
	v_min_f32_e32 v65, 0x49742400, v65
	v_min_f32_e32 v67, 0x49742400, v67
	v_min_f32_e32 v69, 0x49742400, v69
	v_min_f32_e32 v71, 0x49742400, v71
	v_mul_f32_e32 v8, v8, v65
	v_mul_f32_e32 v9, v9, v67
	v_mul_f32_e32 v10, v10, v69
	v_mul_f32_e32 v11, v11, v71
	v_lshlrev_b32_e32 v65, 16, v106
	v_and_b32_e32 v67, 0xffff0000, v106
	v_lshlrev_b32_e32 v69, 16, v107
	v_and_b32_e32 v71, 0xffff0000, v107
	v_mul_f32_e32 v65, 0xbfb8aa3b, v65
	v_mul_f32_e32 v67, 0xbfb8aa3b, v67
	v_mul_f32_e32 v69, 0xbfb8aa3b, v69
	v_mul_f32_e32 v71, 0xbfb8aa3b, v71
	v_exp_f32_e32 v65, v65
	v_exp_f32_e32 v67, v67
	v_exp_f32_e32 v69, v69
	v_exp_f32_e32 v71, v71
	v_add_f32_e32 v65, 1.0, v65
	v_add_f32_e32 v67, 1.0, v67
	v_add_f32_e32 v69, 1.0, v69
	v_add_f32_e32 v71, 1.0, v71
	v_rcp_f32_e32 v65, v65
	v_rcp_f32_e32 v67, v67
	v_rcp_f32_e32 v69, v69
	v_rcp_f32_e32 v71, v71
	v_max_f32_e32 v65, 0x358637bd, v65
	v_max_f32_e32 v67, 0x358637bd, v67
	v_max_f32_e32 v69, 0x358637bd, v69
	v_max_f32_e32 v71, 0x358637bd, v71
	v_mul_f32_e32 v8, v8, v65
	v_mul_f32_e32 v9, v9, v67
	v_mul_f32_e32 v10, v10, v69
	v_mul_f32_e32 v11, v11, v71
	v_lshlrev_b32_e32 v65, 16, v120
	v_and_b32_e32 v67, 0xffff0000, v120
	v_lshlrev_b32_e32 v69, 16, v121
	v_and_b32_e32 v71, 0xffff0000, v121
	v_mul_f32_e32 v65, 0xbfb8aa3b, v65
	v_mul_f32_e32 v67, 0xbfb8aa3b, v67
	v_mul_f32_e32 v69, 0xbfb8aa3b, v69
	v_mul_f32_e32 v71, 0xbfb8aa3b, v71
	v_exp_f32_e32 v65, v65
	v_exp_f32_e32 v67, v67
	v_exp_f32_e32 v69, v69
	v_exp_f32_e32 v71, v71
	v_add_f32_e32 v65, 1.0, v65
	v_add_f32_e32 v67, 1.0, v67
	v_add_f32_e32 v69, 1.0, v69
	v_add_f32_e32 v71, 1.0, v71
	v_min_f32_e32 v65, 0x49742400, v65
	v_min_f32_e32 v67, 0x49742400, v67
	v_min_f32_e32 v69, 0x49742400, v69
	v_min_f32_e32 v71, 0x49742400, v71
	v_mul_f32_e32 v12, v12, v65
	v_mul_f32_e32 v13, v13, v67
	v_mul_f32_e32 v14, v14, v69
	v_mul_f32_e32 v15, v15, v71
	v_lshlrev_b32_e32 v65, 16, v114
	v_and_b32_e32 v67, 0xffff0000, v114
	v_lshlrev_b32_e32 v69, 16, v115
	v_and_b32_e32 v71, 0xffff0000, v115
	v_mul_f32_e32 v65, 0xbfb8aa3b, v65
	v_mul_f32_e32 v67, 0xbfb8aa3b, v67
	v_mul_f32_e32 v69, 0xbfb8aa3b, v69
	v_mul_f32_e32 v71, 0xbfb8aa3b, v71
	v_exp_f32_e32 v65, v65
	v_exp_f32_e32 v67, v67
	v_exp_f32_e32 v69, v69
	v_exp_f32_e32 v71, v71
	v_add_f32_e32 v65, 1.0, v65
	v_add_f32_e32 v67, 1.0, v67
	v_add_f32_e32 v69, 1.0, v69
	v_add_f32_e32 v71, 1.0, v71
	v_rcp_f32_e32 v65, v65
	v_rcp_f32_e32 v67, v67
	v_rcp_f32_e32 v69, v69
	v_rcp_f32_e32 v71, v71
	v_max_f32_e32 v65, 0x358637bd, v65
	v_max_f32_e32 v67, 0x358637bd, v67
	v_max_f32_e32 v69, 0x358637bd, v69
	v_max_f32_e32 v71, 0x358637bd, v71
	v_mul_f32_e32 v12, v12, v65
	v_mul_f32_e32 v13, v13, v67
	v_mul_f32_e32 v14, v14, v69
	v_mul_f32_e32 v15, v15, v71
	v_lshlrev_b32_e32 v65, 16, v128
	v_and_b32_e32 v67, 0xffff0000, v128
	v_lshlrev_b32_e32 v69, 16, v129
	v_and_b32_e32 v71, 0xffff0000, v129
	v_mul_f32_e32 v65, 0xbfb8aa3b, v65
	v_mul_f32_e32 v67, 0xbfb8aa3b, v67
	v_mul_f32_e32 v69, 0xbfb8aa3b, v69
	v_mul_f32_e32 v71, 0xbfb8aa3b, v71
	v_exp_f32_e32 v65, v65
	v_exp_f32_e32 v67, v67
	v_exp_f32_e32 v69, v69
	v_exp_f32_e32 v71, v71
	v_add_f32_e32 v65, 1.0, v65
	v_add_f32_e32 v67, 1.0, v67
	v_add_f32_e32 v69, 1.0, v69
	v_add_f32_e32 v71, 1.0, v71
	v_min_f32_e32 v65, 0x49742400, v65
	v_min_f32_e32 v67, 0x49742400, v67
	v_min_f32_e32 v69, 0x49742400, v69
	v_min_f32_e32 v71, 0x49742400, v71
	v_mul_f32_e32 v16, v16, v65
	v_mul_f32_e32 v17, v17, v67
	v_mul_f32_e32 v18, v18, v69
	v_mul_f32_e32 v19, v19, v71
	v_lshlrev_b32_e32 v65, 16, v122
	v_and_b32_e32 v67, 0xffff0000, v122
	v_lshlrev_b32_e32 v69, 16, v123
	v_and_b32_e32 v71, 0xffff0000, v123
	v_mul_f32_e32 v65, 0xbfb8aa3b, v65
	v_mul_f32_e32 v67, 0xbfb8aa3b, v67
	v_mul_f32_e32 v69, 0xbfb8aa3b, v69
	v_mul_f32_e32 v71, 0xbfb8aa3b, v71
	v_exp_f32_e32 v65, v65
	v_exp_f32_e32 v67, v67
	v_exp_f32_e32 v69, v69
	v_exp_f32_e32 v71, v71
	v_add_f32_e32 v65, 1.0, v65
	v_add_f32_e32 v67, 1.0, v67
	v_add_f32_e32 v69, 1.0, v69
	v_add_f32_e32 v71, 1.0, v71
	v_rcp_f32_e32 v65, v65
	v_rcp_f32_e32 v67, v67
	v_rcp_f32_e32 v69, v69
	v_rcp_f32_e32 v71, v71
	v_max_f32_e32 v65, 0x358637bd, v65
	v_max_f32_e32 v67, 0x358637bd, v67
	v_max_f32_e32 v69, 0x358637bd, v69
	v_max_f32_e32 v71, 0x358637bd, v71
	v_mul_f32_e32 v16, v16, v65
	v_mul_f32_e32 v17, v17, v67
	v_mul_f32_e32 v18, v18, v69
	v_mul_f32_e32 v19, v19, v71
	v_lshlrev_b32_e32 v65, 16, v136
	v_and_b32_e32 v67, 0xffff0000, v136
	v_lshlrev_b32_e32 v69, 16, v137
	v_and_b32_e32 v71, 0xffff0000, v137
	v_mul_f32_e32 v65, 0xbfb8aa3b, v65
	v_mul_f32_e32 v67, 0xbfb8aa3b, v67
	v_mul_f32_e32 v69, 0xbfb8aa3b, v69
	v_mul_f32_e32 v71, 0xbfb8aa3b, v71
	v_exp_f32_e32 v65, v65
	v_exp_f32_e32 v67, v67
	v_exp_f32_e32 v69, v69
	v_exp_f32_e32 v71, v71
	v_add_f32_e32 v65, 1.0, v65
	v_add_f32_e32 v67, 1.0, v67
	v_add_f32_e32 v69, 1.0, v69
	v_add_f32_e32 v71, 1.0, v71
	v_min_f32_e32 v65, 0x49742400, v65
	v_min_f32_e32 v67, 0x49742400, v67
	v_min_f32_e32 v69, 0x49742400, v69
	v_min_f32_e32 v71, 0x49742400, v71
	v_mul_f32_e32 v20, v20, v65
	v_mul_f32_e32 v21, v21, v67
	v_mul_f32_e32 v22, v22, v69
	v_mul_f32_e32 v23, v23, v71
	v_lshlrev_b32_e32 v65, 16, v130
	v_and_b32_e32 v67, 0xffff0000, v130
	v_lshlrev_b32_e32 v69, 16, v131
	v_and_b32_e32 v71, 0xffff0000, v131
	v_mul_f32_e32 v65, 0xbfb8aa3b, v65
	v_mul_f32_e32 v67, 0xbfb8aa3b, v67
	v_mul_f32_e32 v69, 0xbfb8aa3b, v69
	v_mul_f32_e32 v71, 0xbfb8aa3b, v71
	v_exp_f32_e32 v65, v65
	v_exp_f32_e32 v67, v67
	v_exp_f32_e32 v69, v69
	v_exp_f32_e32 v71, v71
	v_add_f32_e32 v65, 1.0, v65
	v_add_f32_e32 v67, 1.0, v67
	v_add_f32_e32 v69, 1.0, v69
	v_add_f32_e32 v71, 1.0, v71
	v_rcp_f32_e32 v65, v65
	v_rcp_f32_e32 v67, v67
	v_rcp_f32_e32 v69, v69
	v_rcp_f32_e32 v71, v71
	v_max_f32_e32 v65, 0x358637bd, v65
	v_max_f32_e32 v67, 0x358637bd, v67
	v_max_f32_e32 v69, 0x358637bd, v69
	v_max_f32_e32 v71, 0x358637bd, v71
	v_mul_f32_e32 v20, v20, v65
	v_mul_f32_e32 v21, v21, v67
	v_mul_f32_e32 v22, v22, v69
	v_mul_f32_e32 v23, v23, v71
	v_lshlrev_b32_e32 v65, 16, v134
	v_and_b32_e32 v67, 0xffff0000, v134
	v_lshlrev_b32_e32 v69, 16, v135
	v_and_b32_e32 v71, 0xffff0000, v135
	v_mul_f32_e32 v65, 0xbfb8aa3b, v65
	v_mul_f32_e32 v67, 0xbfb8aa3b, v67
	v_mul_f32_e32 v69, 0xbfb8aa3b, v69
	v_mul_f32_e32 v71, 0xbfb8aa3b, v71
	v_exp_f32_e32 v65, v65
	v_exp_f32_e32 v67, v67
	v_exp_f32_e32 v69, v69
	v_exp_f32_e32 v71, v71
	v_add_f32_e32 v65, 1.0, v65
	v_add_f32_e32 v67, 1.0, v67
	v_add_f32_e32 v69, 1.0, v69
	v_add_f32_e32 v71, 1.0, v71
	v_min_f32_e32 v65, 0x49742400, v65
	v_min_f32_e32 v67, 0x49742400, v67
	v_min_f32_e32 v69, 0x49742400, v69
	v_min_f32_e32 v71, 0x49742400, v71
	v_mul_f32_e32 v24, v24, v65
	v_mul_f32_e32 v25, v25, v67
	v_mul_f32_e32 v26, v26, v69
	v_mul_f32_e32 v27, v27, v71
	v_lshlrev_b32_e32 v65, 16, v138
	v_and_b32_e32 v67, 0xffff0000, v138
	v_lshlrev_b32_e32 v69, 16, v139
	v_and_b32_e32 v71, 0xffff0000, v139
	v_mul_f32_e32 v65, 0xbfb8aa3b, v65
	v_mul_f32_e32 v67, 0xbfb8aa3b, v67
	v_mul_f32_e32 v69, 0xbfb8aa3b, v69
	v_mul_f32_e32 v71, 0xbfb8aa3b, v71
	v_exp_f32_e32 v65, v65
	v_exp_f32_e32 v67, v67
	v_exp_f32_e32 v69, v69
	v_exp_f32_e32 v71, v71
	v_add_f32_e32 v65, 1.0, v65
	v_add_f32_e32 v67, 1.0, v67
	v_add_f32_e32 v69, 1.0, v69
	v_add_f32_e32 v71, 1.0, v71
	v_rcp_f32_e32 v65, v65
	v_rcp_f32_e32 v67, v67
	v_rcp_f32_e32 v69, v69
	v_rcp_f32_e32 v71, v71
	v_max_f32_e32 v65, 0x358637bd, v65
	v_max_f32_e32 v67, 0x358637bd, v67
	v_max_f32_e32 v69, 0x358637bd, v69
	v_max_f32_e32 v71, 0x358637bd, v71
	v_mul_f32_e32 v24, v24, v65
	v_mul_f32_e32 v25, v25, v67
	v_mul_f32_e32 v26, v26, v69
	v_mul_f32_e32 v27, v27, v71
	v_lshlrev_b32_e32 v65, 16, v126
	v_and_b32_e32 v67, 0xffff0000, v126
	v_lshlrev_b32_e32 v69, 16, v127
	v_and_b32_e32 v71, 0xffff0000, v127
	v_mul_f32_e32 v65, 0xbfb8aa3b, v65
	v_mul_f32_e32 v67, 0xbfb8aa3b, v67
	v_mul_f32_e32 v69, 0xbfb8aa3b, v69
	v_mul_f32_e32 v71, 0xbfb8aa3b, v71
	v_exp_f32_e32 v65, v65
	v_exp_f32_e32 v67, v67
	v_exp_f32_e32 v69, v69
	v_exp_f32_e32 v71, v71
	v_add_f32_e32 v65, 1.0, v65
	v_add_f32_e32 v67, 1.0, v67
	v_add_f32_e32 v69, 1.0, v69
	v_add_f32_e32 v71, 1.0, v71
	v_min_f32_e32 v65, 0x49742400, v65
	v_min_f32_e32 v67, 0x49742400, v67
	v_min_f32_e32 v69, 0x49742400, v69
	v_min_f32_e32 v71, 0x49742400, v71
	v_mul_f32_e32 v28, v28, v65
	v_mul_f32_e32 v29, v29, v67
	v_mul_f32_e32 v30, v30, v69
	v_mul_f32_e32 v31, v31, v71
	v_lshlrev_b32_e32 v65, 16, v132
	v_and_b32_e32 v67, 0xffff0000, v132
	v_lshlrev_b32_e32 v69, 16, v133
	v_and_b32_e32 v71, 0xffff0000, v133
	v_mul_f32_e32 v65, 0xbfb8aa3b, v65
	v_mul_f32_e32 v67, 0xbfb8aa3b, v67
	v_mul_f32_e32 v69, 0xbfb8aa3b, v69
	v_mul_f32_e32 v71, 0xbfb8aa3b, v71
	v_exp_f32_e32 v65, v65
	v_exp_f32_e32 v67, v67
	v_exp_f32_e32 v69, v69
	v_exp_f32_e32 v71, v71
	v_add_f32_e32 v65, 1.0, v65
	v_add_f32_e32 v67, 1.0, v67
	v_add_f32_e32 v69, 1.0, v69
	v_add_f32_e32 v71, 1.0, v71
	v_rcp_f32_e32 v65, v65
	v_rcp_f32_e32 v67, v67
	v_rcp_f32_e32 v69, v69
	v_rcp_f32_e32 v71, v71
	v_max_f32_e32 v65, 0x358637bd, v65
	v_max_f32_e32 v67, 0x358637bd, v67
	v_max_f32_e32 v69, 0x358637bd, v69
	v_max_f32_e32 v71, 0x358637bd, v71
	v_mul_f32_e32 v28, v28, v65
	v_mul_f32_e32 v29, v29, v67
	v_mul_f32_e32 v30, v30, v69
	v_mul_f32_e32 v31, v31, v71
	v_lshlrev_b32_e32 v65, 16, v118
	v_and_b32_e32 v67, 0xffff0000, v118
	v_lshlrev_b32_e32 v69, 16, v119
	v_and_b32_e32 v71, 0xffff0000, v119
	v_mul_f32_e32 v65, 0xbfb8aa3b, v65
	v_mul_f32_e32 v67, 0xbfb8aa3b, v67
	v_mul_f32_e32 v69, 0xbfb8aa3b, v69
	v_mul_f32_e32 v71, 0xbfb8aa3b, v71
	v_exp_f32_e32 v65, v65
	v_exp_f32_e32 v67, v67
	v_exp_f32_e32 v69, v69
	v_exp_f32_e32 v71, v71
	v_add_f32_e32 v65, 1.0, v65
	v_add_f32_e32 v67, 1.0, v67
	v_add_f32_e32 v69, 1.0, v69
	v_add_f32_e32 v71, 1.0, v71
	v_min_f32_e32 v65, 0x49742400, v65
	v_min_f32_e32 v67, 0x49742400, v67
	v_min_f32_e32 v69, 0x49742400, v69
	v_min_f32_e32 v71, 0x49742400, v71
	v_mul_f32_e32 v32, v32, v65
	v_mul_f32_e32 v33, v33, v67
	v_mul_f32_e32 v34, v34, v69
	v_mul_f32_e32 v35, v35, v71
	v_lshlrev_b32_e32 v65, 16, v124
	v_and_b32_e32 v67, 0xffff0000, v124
	v_lshlrev_b32_e32 v69, 16, v125
	v_and_b32_e32 v71, 0xffff0000, v125
	v_mul_f32_e32 v65, 0xbfb8aa3b, v65
	v_mul_f32_e32 v67, 0xbfb8aa3b, v67
	v_mul_f32_e32 v69, 0xbfb8aa3b, v69
	v_mul_f32_e32 v71, 0xbfb8aa3b, v71
	v_exp_f32_e32 v65, v65
	v_exp_f32_e32 v67, v67
	v_exp_f32_e32 v69, v69
	v_exp_f32_e32 v71, v71
	v_add_f32_e32 v65, 1.0, v65
	v_add_f32_e32 v67, 1.0, v67
	v_add_f32_e32 v69, 1.0, v69
	v_add_f32_e32 v71, 1.0, v71
	v_rcp_f32_e32 v65, v65
	v_rcp_f32_e32 v67, v67
	v_rcp_f32_e32 v69, v69
	v_rcp_f32_e32 v71, v71
	v_max_f32_e32 v65, 0x358637bd, v65
	v_max_f32_e32 v67, 0x358637bd, v67
	v_max_f32_e32 v69, 0x358637bd, v69
	v_max_f32_e32 v71, 0x358637bd, v71
	v_mul_f32_e32 v32, v32, v65
	v_mul_f32_e32 v33, v33, v67
	v_mul_f32_e32 v34, v34, v69
	v_mul_f32_e32 v35, v35, v71
	v_lshlrev_b32_e32 v65, 16, v112
	v_and_b32_e32 v67, 0xffff0000, v112
	v_lshlrev_b32_e32 v69, 16, v113
	v_and_b32_e32 v71, 0xffff0000, v113
	v_mul_f32_e32 v65, 0xbfb8aa3b, v65
	v_mul_f32_e32 v67, 0xbfb8aa3b, v67
	v_mul_f32_e32 v69, 0xbfb8aa3b, v69
	v_mul_f32_e32 v71, 0xbfb8aa3b, v71
	v_exp_f32_e32 v65, v65
	v_exp_f32_e32 v67, v67
	v_exp_f32_e32 v69, v69
	v_exp_f32_e32 v71, v71
	v_add_f32_e32 v65, 1.0, v65
	v_add_f32_e32 v67, 1.0, v67
	v_add_f32_e32 v69, 1.0, v69
	v_add_f32_e32 v71, 1.0, v71
	v_min_f32_e32 v65, 0x49742400, v65
	v_min_f32_e32 v67, 0x49742400, v67
	v_min_f32_e32 v69, 0x49742400, v69
	v_min_f32_e32 v71, 0x49742400, v71
	v_mul_f32_e32 v36, v36, v65
	v_mul_f32_e32 v37, v37, v67
	v_mul_f32_e32 v38, v38, v69
	v_mul_f32_e32 v39, v39, v71
	v_lshlrev_b32_e32 v65, 16, v116
	v_and_b32_e32 v67, 0xffff0000, v116
	v_lshlrev_b32_e32 v69, 16, v117
	v_and_b32_e32 v71, 0xffff0000, v117
	v_mul_f32_e32 v65, 0xbfb8aa3b, v65
	v_mul_f32_e32 v67, 0xbfb8aa3b, v67
	v_mul_f32_e32 v69, 0xbfb8aa3b, v69
	v_mul_f32_e32 v71, 0xbfb8aa3b, v71
	v_exp_f32_e32 v65, v65
	v_exp_f32_e32 v67, v67
	v_exp_f32_e32 v69, v69
	v_exp_f32_e32 v71, v71
	v_add_f32_e32 v65, 1.0, v65
	v_add_f32_e32 v67, 1.0, v67
	v_add_f32_e32 v69, 1.0, v69
	v_add_f32_e32 v71, 1.0, v71
	v_rcp_f32_e32 v65, v65
	v_rcp_f32_e32 v67, v67
	v_rcp_f32_e32 v69, v69
	v_rcp_f32_e32 v71, v71
	v_max_f32_e32 v65, 0x358637bd, v65
	v_max_f32_e32 v67, 0x358637bd, v67
	v_max_f32_e32 v69, 0x358637bd, v69
	v_max_f32_e32 v71, 0x358637bd, v71
	v_mul_f32_e32 v36, v36, v65
	v_mul_f32_e32 v37, v37, v67
	v_mul_f32_e32 v38, v38, v69
	v_mul_f32_e32 v39, v39, v71
	v_lshlrev_b32_e32 v65, 16, v104
	v_and_b32_e32 v67, 0xffff0000, v104
	v_lshlrev_b32_e32 v69, 16, v105
	v_and_b32_e32 v71, 0xffff0000, v105
	v_mul_f32_e32 v65, 0xbfb8aa3b, v65
	v_mul_f32_e32 v67, 0xbfb8aa3b, v67
	v_mul_f32_e32 v69, 0xbfb8aa3b, v69
	v_mul_f32_e32 v71, 0xbfb8aa3b, v71
	v_exp_f32_e32 v65, v65
	v_exp_f32_e32 v67, v67
	v_exp_f32_e32 v69, v69
	v_exp_f32_e32 v71, v71
	v_add_f32_e32 v65, 1.0, v65
	v_add_f32_e32 v67, 1.0, v67
	v_add_f32_e32 v69, 1.0, v69
	v_add_f32_e32 v71, 1.0, v71
	v_min_f32_e32 v65, 0x49742400, v65
	v_min_f32_e32 v67, 0x49742400, v67
	v_min_f32_e32 v69, 0x49742400, v69
	v_min_f32_e32 v71, 0x49742400, v71
	v_mul_f32_e32 v40, v40, v65
	v_mul_f32_e32 v41, v41, v67
	v_mul_f32_e32 v42, v42, v69
	v_mul_f32_e32 v43, v43, v71
	v_lshlrev_b32_e32 v65, 16, v108
	v_and_b32_e32 v67, 0xffff0000, v108
	v_lshlrev_b32_e32 v69, 16, v109
	v_and_b32_e32 v71, 0xffff0000, v109
	v_mul_f32_e32 v65, 0xbfb8aa3b, v65
	v_mul_f32_e32 v67, 0xbfb8aa3b, v67
	v_mul_f32_e32 v69, 0xbfb8aa3b, v69
	v_mul_f32_e32 v71, 0xbfb8aa3b, v71
	v_exp_f32_e32 v65, v65
	v_exp_f32_e32 v67, v67
	v_exp_f32_e32 v69, v69
	v_exp_f32_e32 v71, v71
	v_add_f32_e32 v65, 1.0, v65
	v_add_f32_e32 v67, 1.0, v67
	v_add_f32_e32 v69, 1.0, v69
	v_add_f32_e32 v71, 1.0, v71
	v_rcp_f32_e32 v65, v65
	v_rcp_f32_e32 v67, v67
	v_rcp_f32_e32 v69, v69
	v_rcp_f32_e32 v71, v71
	v_max_f32_e32 v65, 0x358637bd, v65
	v_max_f32_e32 v67, 0x358637bd, v67
	v_max_f32_e32 v69, 0x358637bd, v69
	v_max_f32_e32 v71, 0x358637bd, v71
	v_mul_f32_e32 v40, v40, v65
	v_mul_f32_e32 v41, v41, v67
	v_mul_f32_e32 v42, v42, v69
	v_mul_f32_e32 v43, v43, v71
	v_lshlrev_b32_e32 v65, 16, v98
	v_and_b32_e32 v67, 0xffff0000, v98
	v_lshlrev_b32_e32 v69, 16, v99
	v_and_b32_e32 v71, 0xffff0000, v99
	v_mul_f32_e32 v65, 0xbfb8aa3b, v65
	v_mul_f32_e32 v67, 0xbfb8aa3b, v67
	v_mul_f32_e32 v69, 0xbfb8aa3b, v69
	v_mul_f32_e32 v71, 0xbfb8aa3b, v71
	v_exp_f32_e32 v65, v65
	v_exp_f32_e32 v67, v67
	v_exp_f32_e32 v69, v69
	v_exp_f32_e32 v71, v71
	v_add_f32_e32 v65, 1.0, v65
	v_add_f32_e32 v67, 1.0, v67
	v_add_f32_e32 v69, 1.0, v69
	v_add_f32_e32 v71, 1.0, v71
	v_min_f32_e32 v65, 0x49742400, v65
	v_min_f32_e32 v67, 0x49742400, v67
	v_min_f32_e32 v69, 0x49742400, v69
	v_min_f32_e32 v71, 0x49742400, v71
	v_mul_f32_e32 v44, v44, v65
	v_mul_f32_e32 v45, v45, v67
	v_mul_f32_e32 v46, v46, v69
	v_mul_f32_e32 v47, v47, v71
	v_lshlrev_b32_e32 v65, 16, v100
	v_and_b32_e32 v67, 0xffff0000, v100
	v_lshlrev_b32_e32 v69, 16, v101
	v_and_b32_e32 v71, 0xffff0000, v101
	v_mul_f32_e32 v65, 0xbfb8aa3b, v65
	v_mul_f32_e32 v67, 0xbfb8aa3b, v67
	v_mul_f32_e32 v69, 0xbfb8aa3b, v69
	v_mul_f32_e32 v71, 0xbfb8aa3b, v71
	v_exp_f32_e32 v65, v65
	v_exp_f32_e32 v67, v67
	v_exp_f32_e32 v69, v69
	v_exp_f32_e32 v71, v71
	v_add_f32_e32 v65, 1.0, v65
	v_add_f32_e32 v67, 1.0, v67
	v_add_f32_e32 v69, 1.0, v69
	v_add_f32_e32 v71, 1.0, v71
	v_rcp_f32_e32 v65, v65
	v_rcp_f32_e32 v67, v67
	v_rcp_f32_e32 v69, v69
	v_rcp_f32_e32 v71, v71
	v_max_f32_e32 v65, 0x358637bd, v65
	v_max_f32_e32 v67, 0x358637bd, v67
	v_max_f32_e32 v69, 0x358637bd, v69
	v_max_f32_e32 v71, 0x358637bd, v71
	v_mul_f32_e32 v44, v44, v65
	v_mul_f32_e32 v45, v45, v67
	v_mul_f32_e32 v46, v46, v69
	v_mul_f32_e32 v47, v47, v71
	v_lshlrev_b32_e32 v65, 16, v94
	v_and_b32_e32 v67, 0xffff0000, v94
	v_lshlrev_b32_e32 v69, 16, v95
	v_and_b32_e32 v71, 0xffff0000, v95
	v_mul_f32_e32 v65, 0xbfb8aa3b, v65
	v_mul_f32_e32 v67, 0xbfb8aa3b, v67
	v_mul_f32_e32 v69, 0xbfb8aa3b, v69
	v_mul_f32_e32 v71, 0xbfb8aa3b, v71
	v_exp_f32_e32 v65, v65
	v_exp_f32_e32 v67, v67
	v_exp_f32_e32 v69, v69
	v_exp_f32_e32 v71, v71
	v_add_f32_e32 v65, 1.0, v65
	v_add_f32_e32 v67, 1.0, v67
	v_add_f32_e32 v69, 1.0, v69
	v_add_f32_e32 v71, 1.0, v71
	v_min_f32_e32 v65, 0x49742400, v65
	v_min_f32_e32 v67, 0x49742400, v67
	v_min_f32_e32 v69, 0x49742400, v69
	v_min_f32_e32 v71, 0x49742400, v71
	v_mul_f32_e32 v0, v4, v65
	v_mul_f32_e32 v1, v5, v67
	v_mul_f32_e32 v2, v6, v69
	v_mul_f32_e32 v3, v7, v71
	v_lshlrev_b32_e32 v65, 16, v96
	v_and_b32_e32 v67, 0xffff0000, v96
	v_lshlrev_b32_e32 v69, 16, v97
	v_and_b32_e32 v71, 0xffff0000, v97
	v_mul_f32_e32 v65, 0xbfb8aa3b, v65
	v_mul_f32_e32 v67, 0xbfb8aa3b, v67
	v_mul_f32_e32 v69, 0xbfb8aa3b, v69
	v_mul_f32_e32 v71, 0xbfb8aa3b, v71
	v_exp_f32_e32 v65, v65
	v_exp_f32_e32 v67, v67
	v_exp_f32_e32 v69, v69
	v_exp_f32_e32 v71, v71
	v_add_f32_e32 v65, 1.0, v65
	v_add_f32_e32 v67, 1.0, v67
	v_add_f32_e32 v69, 1.0, v69
	v_add_f32_e32 v71, 1.0, v71
	v_rcp_f32_e32 v65, v65
	v_rcp_f32_e32 v67, v67
	v_rcp_f32_e32 v69, v69
	v_rcp_f32_e32 v71, v71
	v_max_f32_e32 v65, 0x358637bd, v65
	v_max_f32_e32 v67, 0x358637bd, v67
	v_max_f32_e32 v69, 0x358637bd, v69
	v_max_f32_e32 v71, 0x358637bd, v71
	v_mul_f32_e32 v0, v0, v65
	v_mul_f32_e32 v1, v1, v67
	v_mul_f32_e32 v2, v2, v69
	v_mul_f32_e32 v3, v3, v71
	s_branch .LBB0_111
